# grid barrier: per-XCD arrival, flat 16-replica release; L1 invalidate issued at arrival (overlaps the wait) instead of after the release
# speedup vs baseline: 1.0598x; 1.0391x over previous
; __device__ __forceinline__ unsigned xb_ld(unsigned* p)              { return __hip_atomic_load(p, __ATOMIC_RELAXED, __HIP_MEMORY_SCOPE_AGENT); }
; __device__ __forceinline__ unsigned xb_add(unsigned* p, unsigned v) { return __hip_atomic_fetch_add(p, v, __ATOMIC_RELAXED, __HIP_MEMORY_SCOPE_AGENT); }
; #define XB_SPIN(cond, bar) do { unsigned _sp = 0; while (cond) { __builtin_amdgcn_s_sleep(1); \
;     if ((++_sp & 255u) == 0u) { if (xb_ld(&(bar)[XB_TMO])) break; if (_sp > XB_SPIN_CAP) { atomicAdd(&(bar)[XB_TMO], 1u); break; } } } } while (0)
; __device__ __forceinline__ void xcd_barrier(const XcdBarrier& b) {
;   asm volatile("s_waitcnt vmcnt(0)" ::: "memory");
;   __syncthreads();
;   if (threadIdx.x == 0) {
;     unsigned* bar = b.bar;
;     __builtin_amdgcn_s_waitcnt(0);
;     unsigned nloc = b.st[0], nx = b.st[1];
;     if (nloc == 0u) { xcd_barrier_complete(bar, b.x, nloc, nx); b.st[0] = nloc; b.st[1] = nx; }
;     const unsigned old = xb_add(&bar[XB_XSUB(b.x)], 1u);
;     const unsigned gen = old / nloc;
;     if (old + 1u == (gen + 1u) * nloc) {
;       __builtin_amdgcn_fence(__ATOMIC_RELEASE, "agent");
;       asm volatile("s_waitcnt vmcnt(0)" ::: "memory");
;       const unsigned og = xb_add(&bar[XB_TOP], 1u);
;       const unsigned tg = og / nx;
;       if (og + 1u == (tg + 1u) * nx) xb_add(&bar[XB_TOPGEN], 1u);
;       else XB_SPIN(xb_ld(&bar[XB_TOPGEN]) == tg, bar);
;       __builtin_amdgcn_fence(__ATOMIC_ACQUIRE, "agent");
;       xb_add(&bar[XB_XGEN(b.x)], 1u);
;       asm volatile("s_waitcnt vmcnt(0)" ::: "memory");
;     } else {
;       XB_SPIN(xb_ld(&bar[XB_XGEN(b.x)]) == gen, bar);
;       __builtin_amdgcn_fence(__ATOMIC_ACQUIRE, "agent");
;       asm volatile("s_waitcnt vmcnt(0)" ::: "memory");
;     }
.LBB0_55:
	s_waitcnt lgkmcnt(0)
	v_readfirstlane_b32 s2, v2
	v_readfirstlane_b32 s3, v0
	v_readlane_b32 s4, v240, 5
	s_lshl_b32 s4, s4, 8
	s_addk_i32 s4, 0x1400
	v_mov_b32_e32 v1, s4
	v_mov_b32_e32 v3, 1
	global_atomic_add v3, v1, v3, s[82:83] sc0
	s_mul_i32 s2, s2, 1
	s_mul_i32 s3, s3, 1
	s_and_b32 s4, s24, 15
	s_lshl_b32 s4, s4, 8
	s_addk_i32 s4, 0x2400
	s_waitcnt vmcnt(0)
	v_readfirstlane_b32 s5, v3
	s_add_i32 s5, s5, 1
	s_cmp_lg_u32 s5, s2
	s_cbranch_scc1 .Lxb0_nm
	buffer_wbl2 sc1
	buffer_inv sc1
	s_waitcnt vmcnt(0)
	s_mov_b64 exec, 0xffff
	v_mbcnt_lo_u32_b32 v1, -1, 0
	v_lshlrev_b32_e32 v1, 8, v1
	v_add_u32_e32 v1, 0x2400, v1
	v_mov_b32_e32 v3, 1
	global_atomic_add v1, v3, s[82:83]
	s_mov_b64 exec, 1
	s_branch .Lxb0_wait

; __device__ __forceinline__ unsigned xb_ld(unsigned* p)              { return __hip_atomic_load(p, __ATOMIC_RELAXED, __HIP_MEMORY_SCOPE_AGENT); }
; __device__ __forceinline__ unsigned xb_add(unsigned* p, unsigned v) { return __hip_atomic_fetch_add(p, v, __ATOMIC_RELAXED, __HIP_MEMORY_SCOPE_AGENT); }
; #define XB_SPIN(cond, bar) do { unsigned _sp = 0; while (cond) { __builtin_amdgcn_s_sleep(1); \
;     if ((++_sp & 255u) == 0u) { if (xb_ld(&(bar)[XB_TMO])) break; if (_sp > XB_SPIN_CAP) { atomicAdd(&(bar)[XB_TMO], 1u); break; } } } } while (0)
; __device__ void phaseA(const Params& p, char* smem) {
;   xcd_queue_run(p.bar + QW_BASE, 464, smem + 2 * GEMM_SMEM + 800, [&](int j, int q) {
;     const int pj = j >> 1, odd = j & 1;
;     int mt, nt;
;     if (q < 384) { mt = q / 3; nt = 7 * pj + odd * 4 + q % 3; }
;     else if (q < 448) { mt = odd * 64 + (q - 384); nt = 7 * pj + 3; }
;     else { mt = 16 * j + (q - 448); nt = 28; }
;     const int m0 = mt * 128, n0 = nt * 128;
;     const u16* xa = p.XB + (size_t)m0 * DM;
;     auto rowf = [&](int r) { return (const void*)(xa + (size_t)r * DM); };
;     auto colf = [&](int c) { int n = n0 + c; if (n > INC - 1) n = INC - 1; return (const void*)(p.WinT + (size_t)n * DM); };
; __device__ __forceinline__ void xcd_barrier(const XcdBarrier& b) {
;     ...
;       else XB_SPIN(xb_ld(&bar[XB_TOPGEN]) == tg, bar);
;       __builtin_amdgcn_fence(__ATOMIC_ACQUIRE, "agent");
;       xb_add(&bar[XB_XGEN(b.x)], 1u);
;       asm volatile("s_waitcnt vmcnt(0)" ::: "memory");
;     } else {
;       XB_SPIN(xb_ld(&bar[XB_XGEN(b.x)]) == gen, bar);
;       __builtin_amdgcn_fence(__ATOMIC_ACQUIRE, "agent");
;       asm volatile("s_waitcnt vmcnt(0)" ::: "memory");
;     }
.Lxb0_wait:
	v_mov_b32_e32 v1, s4
	s_mov_b32 s5, 0
.Lxb0_poll:
	global_load_dword v3, v1, s[82:83] sc1
	s_waitcnt vmcnt(0)
	v_cmp_le_u32_e32 vcc, s3, v3
	s_cbranch_vccnz .Lxb0_done
	s_add_u32 s5, s5, 1
	s_sleep 1
	s_cmp_lt_u32 s5, 0x100000
	s_cbranch_scc1 .Lxb0_poll
.Lxb0_done:
.LBB0_91:
	v_writelane_b32 v240, s24, 42
	s_nop 1
	v_writelane_b32 v240, s25, 43
	s_or_b64 exec, exec, s[0:1]
	s_add_u32 s36, s82, 0x3600
	s_addc_u32 s37, s83, 0
	s_add_u32 s24, s70, 0x80
	s_addc_u32 s25, s71, 0
	v_lshrrev_b32_e32 v133, 1, v128
	v_lshrrev_b32_e32 v160, 3, v128
	v_lshlrev_b32_e32 v123, 3, v128
	s_add_u32 s26, s70, 0x10080
	v_and_b32_e32 v136, 15, v128
	v_lshlrev_b32_e32 v1, 6, v160
	v_xor_b32_e32 v2, v133, v123
	s_addc_u32 s27, s71, 0
	s_waitcnt lgkmcnt(0)
	v_bfe_u32 v0, v128, 6, 1
	v_lshrrev_b32_e32 v170, 7, v128
	v_bfe_u32 v122, v128, 4, 2
	v_mov_b32_e32 v97, 0
	v_bfe_u32 v171, v128, 1, 3
	v_and_or_b32 v161, v2, 56, v1
	v_lshlrev_b32_e32 v1, 6, v136
	s_add_u32 s28, s70, 0x20080
	v_and_b32_e32 v124, 0x70, v140
	v_mov_b32_e32 v125, v97
	v_lshl_or_b32 v162, v0, 12, v1
	v_lshl_or_b32 v164, v170, 12, v1
	v_bitop3_b32 v1, v122, v171, 4 bitop3:0x36
	s_addc_u32 s29, s71, 0
	s_mov_b64 s[20:21], src_shared_base
	v_lshlrev_b32_e32 v138, 11, v160
	v_mov_b32_e32 v139, v97
	v_bitop3_b32 v2, v132, v171, 3 bitop3:0x6c
	v_lshlrev_b32_e32 v165, 3, v1
	v_lshl_or_b32 v126, v170, 6, v136
	v_lshlrev_b32_e32 v116, 6, v0
	v_lshlrev_b32_e32 v134, 2, v122
	v_lshl_add_u64 v[0:1], s[68:69], 0, v[124:125]
	s_add_u32 s30, s70, 0x30080
	s_barrier
	s_getreg_b32 s38, hwreg(HW_REG_XCC_ID, 0, 4)
	v_lshrrev_b32_e32 v129, 6, v128
	v_lshlrev_b32_e32 v163, 3, v2
	v_or_b32_e32 v130, v116, v134
	v_or_b32_e32 v166, 16, v126
	v_or_b32_e32 v167, 32, v126
	v_or_b32_e32 v168, 48, v126
	s_mov_b32 s39, 0
	v_lshl_add_u32 v169, v161, 1, 0
	v_lshl_add_u64 v[98:99], v[0:1], 0, v[138:139]
	v_lshl_add_u64 v[100:101], s[70:71], 0, v[124:125]
	v_lshl_add_u64 v[102:103], s[68:69], 0, v[138:139]
	s_mov_b64 s[22:23], 0x80
	s_addc_u32 s31, s71, 0
	s_mov_b32 s40, 0x10000
	s_mov_b32 s41, 0x20000
	s_mov_b32 s42, 0x30000
	s_movk_i32 s43, 0xe10
	s_movk_i32 s44, 0xc00
	s_movk_i32 s45, 0x1ff
	s_movk_i32 s46, 0xc10
	s_mov_b32 s20, 0x3e000000
	s_mov_b32 s54, 0x3db504f3
	s_movk_i32 s47, 0x1c20
	s_mov_b32 s48, 0x800000
	s_mov_b32 s49, 0x3f317217
	s_mov_b32 s50, 0x7f800000
	v_mov_b32_e32 v117, 0xdef
	v_mov_b32_e32 v118, 0xdcf
	v_mov_b32_e32 v119, 0xdaf
	v_mov_b32_e32 v120, 0x41b17218
	s_branch .LBB0_93

; __device__ __forceinline__ unsigned xb_ld(unsigned* p)              { return __hip_atomic_load(p, __ATOMIC_RELAXED, __HIP_MEMORY_SCOPE_AGENT); }
; __device__ __forceinline__ unsigned xb_add(unsigned* p, unsigned v) { return __hip_atomic_fetch_add(p, v, __ATOMIC_RELAXED, __HIP_MEMORY_SCOPE_AGENT); }
; #define XB_SPIN(cond, bar) do { unsigned _sp = 0; while (cond) { __builtin_amdgcn_s_sleep(1); \
;     if ((++_sp & 255u) == 0u) { if (xb_ld(&(bar)[XB_TMO])) break; if (_sp > XB_SPIN_CAP) { atomicAdd(&(bar)[XB_TMO], 1u); break; } } } } while (0)
; __device__ __forceinline__ void xcd_barrier(const XcdBarrier& b) {
;   asm volatile("s_waitcnt vmcnt(0)" ::: "memory");
;   __syncthreads();
;   if (threadIdx.x == 0) {
;     unsigned* bar = b.bar;
;     __builtin_amdgcn_s_waitcnt(0);
;     unsigned nloc = b.st[0], nx = b.st[1];
;     if (nloc == 0u) { xcd_barrier_complete(bar, b.x, nloc, nx); b.st[0] = nloc; b.st[1] = nx; }
;     const unsigned old = xb_add(&bar[XB_XSUB(b.x)], 1u);
;     const unsigned gen = old / nloc;
;     if (old + 1u == (gen + 1u) * nloc) {
;       __builtin_amdgcn_fence(__ATOMIC_RELEASE, "agent");
;       asm volatile("s_waitcnt vmcnt(0)" ::: "memory");
;       const unsigned og = xb_add(&bar[XB_TOP], 1u);
;       const unsigned tg = og / nx;
;       if (og + 1u == (tg + 1u) * nx) xb_add(&bar[XB_TOPGEN], 1u);
;       else XB_SPIN(xb_ld(&bar[XB_TOPGEN]) == tg, bar);
;       __builtin_amdgcn_fence(__ATOMIC_ACQUIRE, "agent");
;       xb_add(&bar[XB_XGEN(b.x)], 1u);
;       asm volatile("s_waitcnt vmcnt(0)" ::: "memory");
;     } else {
;       XB_SPIN(xb_ld(&bar[XB_XGEN(b.x)]) == gen, bar);
;       __builtin_amdgcn_fence(__ATOMIC_ACQUIRE, "agent");
;       asm volatile("s_waitcnt vmcnt(0)" ::: "memory");
;     }
.LBB0_399:
	s_waitcnt lgkmcnt(0)
	v_readfirstlane_b32 s2, v2
	v_readfirstlane_b32 s3, v0
	v_readlane_b32 s4, v240, 5
	s_lshl_b32 s4, s4, 8
	s_addk_i32 s4, 0x1400
	v_mov_b32_e32 v1, s4
	v_mov_b32_e32 v3, 1
	global_atomic_add v3, v1, v3, s[82:83] sc0
	s_mul_i32 s2, s2, 2
	s_mul_i32 s3, s3, 2
	v_readlane_b32 s4, v240, 42
	s_and_b32 s4, s4, 15
	s_lshl_b32 s4, s4, 8
	s_addk_i32 s4, 0x2400
	s_waitcnt vmcnt(0)
	v_readfirstlane_b32 s5, v3
	s_add_i32 s5, s5, 1
	s_cmp_lg_u32 s5, s2
	s_cbranch_scc1 .Lxb1_nm
	buffer_wbl2 sc1
	buffer_inv sc1
	s_waitcnt vmcnt(0)
	s_mov_b64 exec, 0xffff
	v_mbcnt_lo_u32_b32 v1, -1, 0
	v_lshlrev_b32_e32 v1, 8, v1
	v_add_u32_e32 v1, 0x2400, v1
	v_mov_b32_e32 v3, 1
	global_atomic_add v1, v3, s[82:83]
	s_mov_b64 exec, 1
	s_branch .Lxb1_wait

; __device__ __forceinline__ unsigned xb_ld(unsigned* p)              { return __hip_atomic_load(p, __ATOMIC_RELAXED, __HIP_MEMORY_SCOPE_AGENT); }
; __device__ __forceinline__ unsigned xb_add(unsigned* p, unsigned v) { return __hip_atomic_fetch_add(p, v, __ATOMIC_RELAXED, __HIP_MEMORY_SCOPE_AGENT); }
; #define XB_SPIN(cond, bar) do { unsigned _sp = 0; while (cond) { __builtin_amdgcn_s_sleep(1); \
;     if ((++_sp & 255u) == 0u) { if (xb_ld(&(bar)[XB_TMO])) break; if (_sp > XB_SPIN_CAP) { atomicAdd(&(bar)[XB_TMO], 1u); break; } } } } while (0)
; __device__ void phaseB0(const Params& p, char* smem) {
;   const int nparts = gridDim.x >> 6;
;   if ((int)blockIdx.x >= nparts * 64) return;
;   const int u = blockIdx.x & 63, part = blockIdx.x >> 6;
;   __syncthreads();
;   if (u < 32) recur_unit<128, true, 1>(p, smem, u >> 2, u & 3, p.IMGH + (size_t)u * 128 * IMGH_SZ, part, nparts, 64);
;   else recur_unit<64, false, 1>(p, smem, (u - 32) >> 2, u & 3, p.IMGG + (size_t)(u - 32) * 128 * IMGG_SZ, part, nparts, 64);
; __device__ __forceinline__ void xcd_barrier(const XcdBarrier& b) {
;     ...
;       else XB_SPIN(xb_ld(&bar[XB_TOPGEN]) == tg, bar);
;       __builtin_amdgcn_fence(__ATOMIC_ACQUIRE, "agent");
;       xb_add(&bar[XB_XGEN(b.x)], 1u);
;       asm volatile("s_waitcnt vmcnt(0)" ::: "memory");
;     } else {
;       XB_SPIN(xb_ld(&bar[XB_XGEN(b.x)]) == gen, bar);
;       __builtin_amdgcn_fence(__ATOMIC_ACQUIRE, "agent");
;       asm volatile("s_waitcnt vmcnt(0)" ::: "memory");
;     }
.Lxb1_done:
.LBB0_435:
	s_or_b64 exec, exec, s[0:1]
	v_readlane_b32 s0, v240, 1
	s_andn2_b32 s0, s0, 63
	s_cmp_ge_i32 s40, s0
	s_waitcnt lgkmcnt(0)
	s_barrier
	v_readlane_b32 s1, v240, 2
	s_cbranch_scc1 .LBB0_491
	v_readlane_b32 s0, v240, 1
	v_readlane_b32 s1, v240, 2
	s_lshr_b32 s16, s0, 6
	s_and_b32 s18, s40, 63
	s_lshr_b32 s17, s40, 6
	s_cmp_gt_u32 s18, 31
	s_mov_b64 s[0:1], -1
	s_barrier
	s_cbranch_scc0 .LBB0_461
	s_and_b32 s2, s40, 3
	s_lshl_b32 s3, s2, 6
	v_and_or_b32 v0, v128, 63, s3
	v_lshlrev_b32_e32 v1, 2, v128
	v_add_u32_e32 v2, 0xffffff00, v128
	s_mov_b64 s[0:1], 0
	s_movk_i32 s4, 0xf00
	s_movk_i32 s5, 0x2ff
	s_barrier

; __device__ __forceinline__ unsigned xb_ld(unsigned* p)              { return __hip_atomic_load(p, __ATOMIC_RELAXED, __HIP_MEMORY_SCOPE_AGENT); }
; __device__ __forceinline__ unsigned xb_add(unsigned* p, unsigned v) { return __hip_atomic_fetch_add(p, v, __ATOMIC_RELAXED, __HIP_MEMORY_SCOPE_AGENT); }
; #define XB_SPIN(cond, bar) do { unsigned _sp = 0; while (cond) { __builtin_amdgcn_s_sleep(1); \
;     if ((++_sp & 255u) == 0u) { if (xb_ld(&(bar)[XB_TMO])) break; if (_sp > XB_SPIN_CAP) { atomicAdd(&(bar)[XB_TMO], 1u); break; } } } } while (0)
; __device__ __forceinline__ void xcd_barrier(const XcdBarrier& b) {
;   asm volatile("s_waitcnt vmcnt(0)" ::: "memory");
;   __syncthreads();
;   if (threadIdx.x == 0) {
;     unsigned* bar = b.bar;
;     __builtin_amdgcn_s_waitcnt(0);
;     unsigned nloc = b.st[0], nx = b.st[1];
;     if (nloc == 0u) { xcd_barrier_complete(bar, b.x, nloc, nx); b.st[0] = nloc; b.st[1] = nx; }
;     const unsigned old = xb_add(&bar[XB_XSUB(b.x)], 1u);
;     const unsigned gen = old / nloc;
;     if (old + 1u == (gen + 1u) * nloc) {
;       __builtin_amdgcn_fence(__ATOMIC_RELEASE, "agent");
;       asm volatile("s_waitcnt vmcnt(0)" ::: "memory");
;       const unsigned og = xb_add(&bar[XB_TOP], 1u);
;       const unsigned tg = og / nx;
;       if (og + 1u == (tg + 1u) * nx) xb_add(&bar[XB_TOPGEN], 1u);
;       else XB_SPIN(xb_ld(&bar[XB_TOPGEN]) == tg, bar);
;       __builtin_amdgcn_fence(__ATOMIC_ACQUIRE, "agent");
;       xb_add(&bar[XB_XGEN(b.x)], 1u);
;       asm volatile("s_waitcnt vmcnt(0)" ::: "memory");
;     } else {
;       XB_SPIN(xb_ld(&bar[XB_XGEN(b.x)]) == gen, bar);
;       __builtin_amdgcn_fence(__ATOMIC_ACQUIRE, "agent");
;       asm volatile("s_waitcnt vmcnt(0)" ::: "memory");
;     }
.LBB0_507:
	s_waitcnt lgkmcnt(0)
	v_readfirstlane_b32 s2, v2
	v_readfirstlane_b32 s3, v0
	v_readlane_b32 s4, v240, 5
	s_lshl_b32 s4, s4, 8
	s_addk_i32 s4, 0x1400
	v_mov_b32_e32 v1, s4
	v_mov_b32_e32 v3, 1
	global_atomic_add v3, v1, v3, s[82:83] sc0
	s_mul_i32 s2, s2, 3
	s_mul_i32 s3, s3, 3
	v_readlane_b32 s4, v240, 42
	s_and_b32 s4, s4, 15
	s_lshl_b32 s4, s4, 8
	s_addk_i32 s4, 0x2400
	s_waitcnt vmcnt(0)
	v_readfirstlane_b32 s5, v3
	s_add_i32 s5, s5, 1
	s_cmp_lg_u32 s5, s2
	s_cbranch_scc1 .Lxb2_nm
	buffer_wbl2 sc1
	buffer_inv sc1
	s_waitcnt vmcnt(0)
	s_mov_b64 exec, 0xffff
	v_mbcnt_lo_u32_b32 v1, -1, 0
	v_lshlrev_b32_e32 v1, 8, v1
	v_add_u32_e32 v1, 0x2400, v1
	v_mov_b32_e32 v3, 1
	global_atomic_add v1, v3, s[82:83]
	s_mov_b64 exec, 1
	s_branch .Lxb2_wait

; __device__ void phaseB(const Params& p, char* smem) {
;   if (blockIdx.x >= 64) {
;     ...
;   for (int u = blockIdx.x; u < 64; u += gridDim.x) {
;     __syncthreads();
;     if (u < 32) recur_unit<128, true, 2>(p, smem, u >> 2, u & 3, p.IMGH + (size_t)u * 128 * IMGH_SZ, 0, 1, SEQ / 16);
;     else recur_unit<64, false, 2>(p, smem, (u - 32) >> 2, u & 3, p.IMGG + (size_t)(u - 32) * 128 * IMGG_SZ, 0, 1, SEQ / 16);
.Lxb2_done:
.LBB0_543:
	s_or_b64 exec, exec, s[0:1]
	v_cmp_gt_u32_e64 s[2:3], 16, v128
	s_mov_b64 s[0:1], -1
	s_cmp_gt_u32 s40, 63
	v_writelane_b32 v240, s2, 44
	s_waitcnt lgkmcnt(0)
	s_barrier
	v_writelane_b32 v240, s3, 45
	s_cbranch_scc1 .LBB0_774
	s_movk_i32 s0, 0x1e0
	v_and_or_b32 v137, v133, s0, v136
	s_movk_i32 s0, 0x310
	s_add_u32 s54, s82, 0x200
	v_cmp_gt_u32_e64 s[8:9], s0, v128
	s_movk_i32 s0, 0x210
	s_addc_u32 s55, s83, 0
	v_cmp_gt_u32_e64 s[10:11], s0, v128
	s_movk_i32 s0, 0x110
	s_add_u32 s60, s82, 0x1000
	v_cmp_gt_u32_e64 s[12:13], s0, v128
	v_and_b32_e32 v144, 0x78, v123
	s_movk_i32 s0, 0x88
	s_addc_u32 s61, s83, 0
	s_waitcnt vmcnt(0)
	v_mad_u32_u24 v0, v132, s0, v144
	s_movk_i32 s0, 0x48
	s_add_u32 s66, s82, 0x1100
	v_lshl_add_u32 v139, v0, 1, 0
	v_mad_u32_u24 v0, v136, s0, v134
	s_addc_u32 s67, s83, 0
	v_lshl_add_u32 v145, v0, 1, 0
	v_or_b32_e32 v0, 2, v134
	s_add_u32 s68, s82, 0x1200
	v_cmp_gt_u32_e64 s[18:19], v0, v136
	v_or_b32_e32 v0, 3, v134
	s_addc_u32 s69, s83, 0
	v_cmp_gt_u32_e64 s[20:21], v0, v136
	v_mul_u32_u24_e32 v0, 20, v137
	v_lshlrev_b32_e32 v1, 1, v134
	s_add_u32 s70, s82, 0x1300
	v_lshlrev_b32_e32 v0, 1, v0
	v_add_u32_e32 v172, 0, v1
	s_movk_i32 s2, 0x220
	s_addc_u32 s71, s83, 0
	v_add3_u32 v147, 0, v0, v1
	v_add_u32_e32 v173, v172, v0
	v_mad_u32_u24 v0, v122, s2, v137
	s_add_u32 s2, s82, 0x3400
	s_addc_u32 s3, s83, 0
	s_movk_i32 s0, 0x3c0
	v_writelane_b32 v240, s2, 46
	v_cmp_gt_u32_e64 s[24:25], s0, v128
	s_movk_i32 s0, 0x2c0
	v_writelane_b32 v240, s3, 47
	s_add_u32 s2, s82, 0x3500
	v_cmp_gt_u32_e64 s[26:27], s0, v128
	s_movk_i32 s0, 0x1c0
	s_addc_u32 s3, s83, 0
	v_cmp_gt_u32_e64 s[28:29], s0, v128
	s_movk_i32 s0, 0xc0
	v_writelane_b32 v240, s2, 48
	v_cmp_gt_u32_e64 s[30:31], s0, v128
	s_add_i32 s0, 0, 0x10300
	v_writelane_b32 v240, s3, 49
	v_mov_b32_e32 v143, 0
	v_lshl_add_u32 v177, v0, 1, 0
	v_lshlrev_b32_e32 v178, 11, v132
	v_mul_u32_u24_e32 v0, 0x88, v136
	v_lshlrev_b32_e32 v142, 1, v144
	v_writelane_b32 v240, s0, 50
	s_add_i32 s0, 0, 0x10304
	v_mov_b32_e32 v141, v143
	v_add_u32_e32 v146, 16, v132
	s_mov_b32 s1, 0
	v_cmp_gt_u32_e64 s[14:15], v134, v136
	v_cmp_lt_u32_e64 s[16:17], v134, v136
	v_mul_u32_u24_e32 v174, 40, v136
	v_lshl_add_u32 v175, v122, 3, v172
	v_cmp_eq_u32_e64 s[22:23], 0, v136
	v_and_b32_e32 v176, 0x3c0, v128
	v_add_u32_e32 v179, 0x8000, v178
	v_lshl_add_u32 v180, v0, 1, v172
	v_lshl_add_u64 v[148:149], s[88:89], 0, v[142:143]
	v_writelane_b32 v240, s0, 51
	v_mov_b32_e32 v181, 0x1000
	v_mov_b32_e32 v182, 0x2000
	v_mov_b32_e32 v183, 1
	s_brev_b32 s4, 60
	s_mov_b32 s5, 0x800000
	v_mov_b32_e32 v184, 0x1c20
	s_mov_b32 s0, s40
	s_branch .LBB0_546

; #define LAS __attribute__((address_space(3)))
; __device__ __forceinline__ unsigned xb_ld(unsigned* p)              { return __hip_atomic_load(p, __ATOMIC_RELAXED, __HIP_MEMORY_SCOPE_AGENT); }
; __device__ __forceinline__ unsigned xb_add(unsigned* p, unsigned v) { return __hip_atomic_fetch_add(p, v, __ATOMIC_RELAXED, __HIP_MEMORY_SCOPE_AGENT); }
; __device__ __forceinline__ unsigned xb_xcc_id() { return (unsigned)__builtin_amdgcn_s_getreg((3 << 11) | 20) & 0xFu; }
; #define XB_SPIN(cond, bar) do { unsigned _sp = 0; while (cond) { __builtin_amdgcn_s_sleep(1); \
;     if ((++_sp & 255u) == 0u) { if (xb_ld(&(bar)[XB_TMO])) break; if (_sp > XB_SPIN_CAP) { atomicAdd(&(bar)[XB_TMO], 1u); break; } } } } while (0)
; __device__ __forceinline__ void xcd_barrier(const XcdBarrier& b) {
;   asm volatile("s_waitcnt vmcnt(0)" ::: "memory");
;   __syncthreads();
;   if (threadIdx.x == 0) {
;     unsigned* bar = b.bar;
;     __builtin_amdgcn_s_waitcnt(0);
;     unsigned nloc = b.st[0], nx = b.st[1];
;     if (nloc == 0u) { xcd_barrier_complete(bar, b.x, nloc, nx); b.st[0] = nloc; b.st[1] = nx; }
;     const unsigned old = xb_add(&bar[XB_XSUB(b.x)], 1u);
;     const unsigned gen = old / nloc;
;     if (old + 1u == (gen + 1u) * nloc) {
;       __builtin_amdgcn_fence(__ATOMIC_RELEASE, "agent");
;       asm volatile("s_waitcnt vmcnt(0)" ::: "memory");
;       const unsigned og = xb_add(&bar[XB_TOP], 1u);
;       const unsigned tg = og / nx;
;       if (og + 1u == (tg + 1u) * nx) xb_add(&bar[XB_TOPGEN], 1u);
;       else XB_SPIN(xb_ld(&bar[XB_TOPGEN]) == tg, bar);
;       __builtin_amdgcn_fence(__ATOMIC_ACQUIRE, "agent");
;       xb_add(&bar[XB_XGEN(b.x)], 1u);
;       asm volatile("s_waitcnt vmcnt(0)" ::: "memory");
;     } else {
;       XB_SPIN(xb_ld(&bar[XB_XGEN(b.x)]) == gen, bar);
;       __builtin_amdgcn_fence(__ATOMIC_ACQUIRE, "agent");
;       asm volatile("s_waitcnt vmcnt(0)" ::: "memory");
;     }
; __device__ void mid_barrier(const Params& p, char* smem) {
;   XcdBarrier b; b.bar = p.bar; b.x = xb_xcc_id(); b.st = (volatile LAS unsigned*)(smem + 2 * GEMM_SMEM + 768);
;   xcd_barrier(b);
; }
.LBB0_723:
	s_waitcnt lgkmcnt(0)
	v_readfirstlane_b32 s0, v114
	v_readfirstlane_b32 s2, v112
	v_readlane_b32 s3, v240, 5
	s_lshl_b32 s3, s3, 8
	s_addk_i32 s3, 0x1400
	v_mov_b32_e32 v113, s3
	v_mov_b32_e32 v115, 1
	global_atomic_add v115, v113, v115, s[82:83] sc0
	s_mul_i32 s0, s0, 4
	s_mul_i32 s2, s2, 4
	v_readlane_b32 s3, v240, 42
	s_and_b32 s3, s3, 15
	s_lshl_b32 s3, s3, 8
	s_addk_i32 s3, 0x2400
	s_waitcnt vmcnt(0)
	v_readfirstlane_b32 s6, v115
	s_add_i32 s6, s6, 1
	s_cmp_lg_u32 s6, s0
	s_cbranch_scc1 .Lxb3_nm
	buffer_wbl2 sc1
	buffer_inv sc1
	s_waitcnt vmcnt(0)
	s_mov_b64 exec, 0xffff
	v_mbcnt_lo_u32_b32 v113, -1, 0
	v_lshlrev_b32_e32 v113, 8, v113
	v_add_u32_e32 v113, 0x2400, v113
	v_mov_b32_e32 v115, 1
	global_atomic_add v113, v115, s[82:83]
	s_mov_b64 exec, 1
	s_branch .Lxb3_wait

; __device__ __forceinline__ unsigned xb_ld(unsigned* p)              { return __hip_atomic_load(p, __ATOMIC_RELAXED, __HIP_MEMORY_SCOPE_AGENT); }
; __device__ __forceinline__ unsigned xb_add(unsigned* p, unsigned v) { return __hip_atomic_fetch_add(p, v, __ATOMIC_RELAXED, __HIP_MEMORY_SCOPE_AGENT); }
; #define XB_SPIN(cond, bar) do { unsigned _sp = 0; while (cond) { __builtin_amdgcn_s_sleep(1); \
;     if ((++_sp & 255u) == 0u) { if (xb_ld(&(bar)[XB_TMO])) break; if (_sp > XB_SPIN_CAP) { atomicAdd(&(bar)[XB_TMO], 1u); break; } } } } while (0)
; template <int DK, bool HG, int MODE>
; __device__ void recur_unit(const Params& p, char* smem, int b, int h, char* img, int nstart, int nstep, int nend) {
;     ...
;       if (n == 62) mid_barrier(p, smem);
; __device__ __forceinline__ void xcd_barrier(const XcdBarrier& b) {
;     ...
;       else XB_SPIN(xb_ld(&bar[XB_TOPGEN]) == tg, bar);
;       __builtin_amdgcn_fence(__ATOMIC_ACQUIRE, "agent");
;       xb_add(&bar[XB_XGEN(b.x)], 1u);
;       asm volatile("s_waitcnt vmcnt(0)" ::: "memory");
;     } else {
;       XB_SPIN(xb_ld(&bar[XB_XGEN(b.x)]) == gen, bar);
;       __builtin_amdgcn_fence(__ATOMIC_ACQUIRE, "agent");
;       asm volatile("s_waitcnt vmcnt(0)" ::: "memory");
;     }
.Lxb3_wait:
	v_mov_b32_e32 v113, s3
	s_mov_b32 s6, 0
.Lxb3_poll:
	global_load_dword v115, v113, s[82:83] sc1
	s_waitcnt vmcnt(0)
	v_cmp_le_u32_e32 vcc, s2, v115
	s_cbranch_vccnz .Lxb3_done
	s_add_u32 s6, s6, 1
	s_sleep 1
	s_cmp_lt_u32 s6, 0x100000
	s_cbranch_scc1 .Lxb3_poll
.Lxb3_done:
.LBB0_759:
	s_or_b64 exec, exec, s[38:39]
	s_waitcnt lgkmcnt(0)
	s_barrier
	s_cmp_eq_u32 s4, 0
	s_cbranch_scc1 .Lrec_hg_midret
	s_branch .Lrec_gla_midret

; __device__ __forceinline__ unsigned xb_ld(unsigned* p)              { return __hip_atomic_load(p, __ATOMIC_RELAXED, __HIP_MEMORY_SCOPE_AGENT); }
; __device__ __forceinline__ unsigned xb_add(unsigned* p, unsigned v) { return __hip_atomic_fetch_add(p, v, __ATOMIC_RELAXED, __HIP_MEMORY_SCOPE_AGENT); }
; #define XB_SPIN(cond, bar) do { unsigned _sp = 0; while (cond) { __builtin_amdgcn_s_sleep(1); \
;     if ((++_sp & 255u) == 0u) { if (xb_ld(&(bar)[XB_TMO])) break; if (_sp > XB_SPIN_CAP) { atomicAdd(&(bar)[XB_TMO], 1u); break; } } } } while (0)
; __device__ void phaseB(const Params& p, char* smem) {
;     ...
;     mid_barrier(p, smem);
; __device__ __forceinline__ void xcd_barrier(const XcdBarrier& b) {
;   asm volatile("s_waitcnt vmcnt(0)" ::: "memory");
;   __syncthreads();
;   if (threadIdx.x == 0) {
;     unsigned* bar = b.bar;
;     __builtin_amdgcn_s_waitcnt(0);
;     unsigned nloc = b.st[0], nx = b.st[1];
;     if (nloc == 0u) { xcd_barrier_complete(bar, b.x, nloc, nx); b.st[0] = nloc; b.st[1] = nx; }
;     const unsigned old = xb_add(&bar[XB_XSUB(b.x)], 1u);
;     const unsigned gen = old / nloc;
;     if (old + 1u == (gen + 1u) * nloc) {
;       __builtin_amdgcn_fence(__ATOMIC_RELEASE, "agent");
;       asm volatile("s_waitcnt vmcnt(0)" ::: "memory");
;       const unsigned og = xb_add(&bar[XB_TOP], 1u);
;       const unsigned tg = og / nx;
;       if (og + 1u == (tg + 1u) * nx) xb_add(&bar[XB_TOPGEN], 1u);
;       else XB_SPIN(xb_ld(&bar[XB_TOPGEN]) == tg, bar);
;       __builtin_amdgcn_fence(__ATOMIC_ACQUIRE, "agent");
;       xb_add(&bar[XB_XGEN(b.x)], 1u);
;       asm volatile("s_waitcnt vmcnt(0)" ::: "memory");
;     } else {
;       XB_SPIN(xb_ld(&bar[XB_XGEN(b.x)]) == gen, bar);
;       __builtin_amdgcn_fence(__ATOMIC_ACQUIRE, "agent");
;       asm volatile("s_waitcnt vmcnt(0)" ::: "memory");
;     }
.LBB0_853:
	s_waitcnt lgkmcnt(0)
	v_readfirstlane_b32 s2, v2
	v_readfirstlane_b32 s3, v0
	v_readlane_b32 s4, v240, 5
	s_lshl_b32 s4, s4, 8
	s_addk_i32 s4, 0x1400
	v_mov_b32_e32 v1, s4
	v_mov_b32_e32 v3, 1
	global_atomic_add v3, v1, v3, s[82:83] sc0
	s_mul_i32 s2, s2, 4
	s_mul_i32 s3, s3, 4
	v_readlane_b32 s4, v240, 42
	s_and_b32 s4, s4, 15
	s_lshl_b32 s4, s4, 8
	s_addk_i32 s4, 0x2400
	s_waitcnt vmcnt(0)
	v_readfirstlane_b32 s5, v3
	s_add_i32 s5, s5, 1
	s_cmp_lg_u32 s5, s2
	s_cbranch_scc1 .Lxb4_nm
	buffer_wbl2 sc1
	buffer_inv sc1
	s_waitcnt vmcnt(0)
	s_mov_b64 exec, 0xffff
	v_mbcnt_lo_u32_b32 v1, -1, 0
	v_lshlrev_b32_e32 v1, 8, v1
	v_add_u32_e32 v1, 0x2400, v1
	v_mov_b32_e32 v3, 1
	global_atomic_add v1, v3, s[82:83]
	s_mov_b64 exec, 1
	s_branch .Lxb4_wait

; __device__ void phaseC(const Params& p, char* smem, int which) {
;   for (int half = 0; half <= which; half++)
;   xcd_queue_run(p.bar + QW_BASE + 512 + 32 * half, half ? 72 : 56, smem + 2 * GEMM_SMEM + 800, [&](int j, int q) {
;     const int mt = half ? ((q / 9) * 16 + 7 + q % 9) : ((q / 7) * 16 + q % 7), nt = j;
;     const int m0 = mt * 128, n0 = nt * 128;
;     auto rowf = [&](int r) { return (const void*)(p.O + (size_t)(m0 + r) * DM); };
;     auto colf = [&](int c) { return (const void*)(p.WoutT + (size_t)(n0 + c) * DM); };
.Lxb4_done:
.LBB0_889:
	s_or_b64 exec, exec, s[0:1]
	s_add_u32 s26, s82, 0x3e00
	v_readlane_b32 s4, v240, 24
	s_addc_u32 s27, s83, 0
	v_readlane_b32 s5, v240, 25
	s_mov_b64 s[0:1], src_shared_base
	s_waitcnt lgkmcnt(0)
	s_barrier
	v_mov_b32_e32 v103, 0
	v_lshlrev_b32_e32 v102, 2, v130
	v_lshl_add_u64 v[106:107], s[4:5], 0, v[124:125]
	s_getreg_b32 s28, hwreg(HW_REG_XCC_ID, 0, 4)
	s_add_u32 s4, s4, 0x80
	v_lshl_add_u64 v[104:105], s[90:91], 0, v[102:103]
	v_lshl_add_u64 v[108:109], s[72:73], 0, v[124:125]
	s_mov_b64 s[2:3], 0x80
	s_addc_u32 s5, s5, 0
	s_mov_b32 s7, 0
	s_mov_b64 s[8:9], 0x10000
	s_mov_b64 s[10:11], 0x20000
	s_mov_b64 s[12:13], 0x30000
	s_mov_b32 s29, 0x92492493
	s_movk_i32 s30, 0xfc00
	s_mov_b32 s0, 0x3f9837f0
	s_mov_b32 s31, s28
	s_mov_b32 s36, 0
	s_branch .LBB0_891

; __device__ __forceinline__ unsigned xb_ld(unsigned* p)              { return __hip_atomic_load(p, __ATOMIC_RELAXED, __HIP_MEMORY_SCOPE_AGENT); }
; __device__ __forceinline__ unsigned xb_add(unsigned* p, unsigned v) { return __hip_atomic_fetch_add(p, v, __ATOMIC_RELAXED, __HIP_MEMORY_SCOPE_AGENT); }
; #define XB_SPIN(cond, bar) do { unsigned _sp = 0; while (cond) { __builtin_amdgcn_s_sleep(1); \
;     if ((++_sp & 255u) == 0u) { if (xb_ld(&(bar)[XB_TMO])) break; if (_sp > XB_SPIN_CAP) { atomicAdd(&(bar)[XB_TMO], 1u); break; } } } } while (0)
; __device__ __forceinline__ void xcd_barrier(const XcdBarrier& b) {
;     ...
;     unsigned nloc = b.st[0], nx = b.st[1];
;     if (nloc == 0u) { xcd_barrier_complete(bar, b.x, nloc, nx); b.st[0] = nloc; b.st[1] = nx; }
;     const unsigned old = xb_add(&bar[XB_XSUB(b.x)], 1u);
;     const unsigned gen = old / nloc;
;     if (old + 1u == (gen + 1u) * nloc) {
;       __builtin_amdgcn_fence(__ATOMIC_RELEASE, "agent");
;       asm volatile("s_waitcnt vmcnt(0)" ::: "memory");
;       const unsigned og = xb_add(&bar[XB_TOP], 1u);
;       const unsigned tg = og / nx;
;       if (og + 1u == (tg + 1u) * nx) xb_add(&bar[XB_TOPGEN], 1u);
;       else XB_SPIN(xb_ld(&bar[XB_TOPGEN]) == tg, bar);
;       __builtin_amdgcn_fence(__ATOMIC_ACQUIRE, "agent");
;       xb_add(&bar[XB_XGEN(b.x)], 1u);
;       asm volatile("s_waitcnt vmcnt(0)" ::: "memory");
;     } else {
;       XB_SPIN(xb_ld(&bar[XB_XGEN(b.x)]) == gen, bar);
;       __builtin_amdgcn_fence(__ATOMIC_ACQUIRE, "agent");
;       asm volatile("s_waitcnt vmcnt(0)" ::: "memory");
;     }
;   }
;   __syncthreads();
; }
.Lxb5_done:
.LBB0_970:
	s_or_b64 exec, exec, s[0:1]
	s_waitcnt lgkmcnt(0)
	s_barrier

; __device__ __forceinline__ unsigned xb_ld(unsigned* p)              { return __hip_atomic_load(p, __ATOMIC_RELAXED, __HIP_MEMORY_SCOPE_AGENT); }
; __device__ __forceinline__ unsigned xb_add(unsigned* p, unsigned v) { return __hip_atomic_fetch_add(p, v, __ATOMIC_RELAXED, __HIP_MEMORY_SCOPE_AGENT); }
; #define XB_SPIN(cond, bar) do { unsigned _sp = 0; while (cond) { __builtin_amdgcn_s_sleep(1); \
;     if ((++_sp & 255u) == 0u) { if (xb_ld(&(bar)[XB_TMO])) break; if (_sp > XB_SPIN_CAP) { atomicAdd(&(bar)[XB_TMO], 1u); break; } } } } while (0)
; __device__ __forceinline__ void xcd_barrier(const XcdBarrier& b) {
;     ...
;     unsigned nloc = b.st[0], nx = b.st[1];
;     if (nloc == 0u) { xcd_barrier_complete(bar, b.x, nloc, nx); b.st[0] = nloc; b.st[1] = nx; }
;     const unsigned old = xb_add(&bar[XB_XSUB(b.x)], 1u);
;     const unsigned gen = old / nloc;
;     if (old + 1u == (gen + 1u) * nloc) {
;       __builtin_amdgcn_fence(__ATOMIC_RELEASE, "agent");
;       asm volatile("s_waitcnt vmcnt(0)" ::: "memory");
;       const unsigned og = xb_add(&bar[XB_TOP], 1u);
;       const unsigned tg = og / nx;
;       if (og + 1u == (tg + 1u) * nx) xb_add(&bar[XB_TOPGEN], 1u);
;       else XB_SPIN(xb_ld(&bar[XB_TOPGEN]) == tg, bar);
;       __builtin_amdgcn_fence(__ATOMIC_ACQUIRE, "agent");
;       xb_add(&bar[XB_XGEN(b.x)], 1u);
;       asm volatile("s_waitcnt vmcnt(0)" ::: "memory");
;     } else {
;       XB_SPIN(xb_ld(&bar[XB_XGEN(b.x)]) == gen, bar);
;       __builtin_amdgcn_fence(__ATOMIC_ACQUIRE, "agent");
;       asm volatile("s_waitcnt vmcnt(0)" ::: "memory");
;     }
.LBB0_987:
	s_waitcnt lgkmcnt(0)
	v_readfirstlane_b32 s2, v2
	v_readfirstlane_b32 s3, v0
	v_readlane_b32 s4, v240, 5
	s_lshl_b32 s4, s4, 8
	s_addk_i32 s4, 0x1400
	v_mov_b32_e32 v1, s4
	v_mov_b32_e32 v3, 1
	global_atomic_add v3, v1, v3, s[82:83] sc0
	s_mul_i32 s2, s2, 5
	s_mul_i32 s3, s3, 5
	v_readlane_b32 s4, v240, 42
	s_and_b32 s4, s4, 15
	s_lshl_b32 s4, s4, 8
	s_addk_i32 s4, 0x2400
	s_waitcnt vmcnt(0)
	v_readfirstlane_b32 s5, v3
	s_add_i32 s5, s5, 1
	s_cmp_lg_u32 s5, s2
	s_cbranch_scc1 .Lxb6_nm
	buffer_wbl2 sc1
	buffer_inv sc1
	s_waitcnt vmcnt(0)
	s_mov_b64 exec, 0xffff
	v_mbcnt_lo_u32_b32 v1, -1, 0
	v_lshlrev_b32_e32 v1, 8, v1
	v_add_u32_e32 v1, 0x2400, v1
	v_mov_b32_e32 v3, 1
	global_atomic_add v1, v3, s[82:83]
	s_mov_b64 exec, 1
	s_branch .Lxb6_wait

; __device__ __forceinline__ unsigned xb_ld(unsigned* p)              { return __hip_atomic_load(p, __ATOMIC_RELAXED, __HIP_MEMORY_SCOPE_AGENT); }
; __device__ __forceinline__ unsigned xb_add(unsigned* p, unsigned v) { return __hip_atomic_fetch_add(p, v, __ATOMIC_RELAXED, __HIP_MEMORY_SCOPE_AGENT); }
; #define XB_SPIN(cond, bar) do { unsigned _sp = 0; while (cond) { __builtin_amdgcn_s_sleep(1); \
;     if ((++_sp & 255u) == 0u) { if (xb_ld(&(bar)[XB_TMO])) break; if (_sp > XB_SPIN_CAP) { atomicAdd(&(bar)[XB_TMO], 1u); break; } } } } while (0)
; __device__ void phaseC(const Params& p, char* smem, int which) {
;   for (int half = 0; half <= which; half++)
;   xcd_queue_run(p.bar + QW_BASE + 512 + 32 * half, half ? 72 : 56, smem + 2 * GEMM_SMEM + 800, [&](int j, int q) {
;     const int mt = half ? ((q / 9) * 16 + 7 + q % 9) : ((q / 7) * 16 + q % 7), nt = j;
;     const int m0 = mt * 128, n0 = nt * 128;
; __device__ __forceinline__ void xcd_barrier(const XcdBarrier& b) {
;     ...
;     unsigned nloc = b.st[0], nx = b.st[1];
;     if (nloc == 0u) { xcd_barrier_complete(bar, b.x, nloc, nx); b.st[0] = nloc; b.st[1] = nx; }
;     const unsigned old = xb_add(&bar[XB_XSUB(b.x)], 1u);
;     const unsigned gen = old / nloc;
;     if (old + 1u == (gen + 1u) * nloc) {
;       __builtin_amdgcn_fence(__ATOMIC_RELEASE, "agent");
;       asm volatile("s_waitcnt vmcnt(0)" ::: "memory");
;       const unsigned og = xb_add(&bar[XB_TOP], 1u);
;       const unsigned tg = og / nx;
;       if (og + 1u == (tg + 1u) * nx) xb_add(&bar[XB_TOPGEN], 1u);
;       else XB_SPIN(xb_ld(&bar[XB_TOPGEN]) == tg, bar);
;       __builtin_amdgcn_fence(__ATOMIC_ACQUIRE, "agent");
;       xb_add(&bar[XB_XGEN(b.x)], 1u);
;       asm volatile("s_waitcnt vmcnt(0)" ::: "memory");
;     } else {
;       XB_SPIN(xb_ld(&bar[XB_XGEN(b.x)]) == gen, bar);
;       __builtin_amdgcn_fence(__ATOMIC_ACQUIRE, "agent");
;       asm volatile("s_waitcnt vmcnt(0)" ::: "memory");
;     }
;   }
;   __syncthreads();
; }
.Lxb6_done:
.LBB0_1023:
	s_or_b64 exec, exec, s[0:1]
	s_add_u32 s28, s82, 0x3e00
	v_readlane_b32 s4, v240, 24
	s_addc_u32 s29, s83, 0
	v_readlane_b32 s5, v240, 25
	s_mov_b64 s[0:1], src_shared_base
	v_mov_b32_e32 v97, 0
	v_lshlrev_b32_e32 v96, 2, v130
	v_lshl_add_u64 v[102:103], s[4:5], 0, v[124:125]
	s_add_u32 s4, s4, 0x80
	v_mov_b32_e32 v99, v97
	v_lshl_add_u64 v[100:101], s[90:91], 0, v[96:97]
	v_lshl_add_u64 v[104:105], s[72:73], 0, v[124:125]
	s_mov_b64 s[2:3], 0x80
	s_addc_u32 s5, s5, 0
	s_mov_b32 s9, 0
	s_mov_b64 s[10:11], 0x20000
	s_mov_b64 s[12:13], 0x30000
	s_mov_b32 s30, 0x38e38e39
	s_mov_b32 s31, 0x92492493
	s_movk_i32 s36, 0xfc00
	s_mov_b32 s0, 0x3f9837f0
	s_mov_b64 s[14:15], 0xc0
	s_mov_b32 s37, 0
	s_waitcnt lgkmcnt(0)
	s_barrier
	s_branch .LBB0_1025

; __device__ __forceinline__ unsigned xb_ld(unsigned* p)              { return __hip_atomic_load(p, __ATOMIC_RELAXED, __HIP_MEMORY_SCOPE_AGENT); }
; __device__ __forceinline__ unsigned xb_add(unsigned* p, unsigned v) { return __hip_atomic_fetch_add(p, v, __ATOMIC_RELAXED, __HIP_MEMORY_SCOPE_AGENT); }
; #define XB_SPIN(cond, bar) do { unsigned _sp = 0; while (cond) { __builtin_amdgcn_s_sleep(1); \
;     if ((++_sp & 255u) == 0u) { if (xb_ld(&(bar)[XB_TMO])) break; if (_sp > XB_SPIN_CAP) { atomicAdd(&(bar)[XB_TMO], 1u); break; } } } } while (0)
; __device__ __forceinline__ void xcd_barrier(const XcdBarrier& b) {
;     ...
;     unsigned nloc = b.st[0], nx = b.st[1];
;     if (nloc == 0u) { xcd_barrier_complete(bar, b.x, nloc, nx); b.st[0] = nloc; b.st[1] = nx; }
;     const unsigned old = xb_add(&bar[XB_XSUB(b.x)], 1u);
;     const unsigned gen = old / nloc;
;     if (old + 1u == (gen + 1u) * nloc) {
;       __builtin_amdgcn_fence(__ATOMIC_RELEASE, "agent");
;       asm volatile("s_waitcnt vmcnt(0)" ::: "memory");
;       const unsigned og = xb_add(&bar[XB_TOP], 1u);
;       const unsigned tg = og / nx;
;       if (og + 1u == (tg + 1u) * nx) xb_add(&bar[XB_TOPGEN], 1u);
;       else XB_SPIN(xb_ld(&bar[XB_TOPGEN]) == tg, bar);
;       __builtin_amdgcn_fence(__ATOMIC_ACQUIRE, "agent");
;       xb_add(&bar[XB_XGEN(b.x)], 1u);
;       asm volatile("s_waitcnt vmcnt(0)" ::: "memory");
;     } else {
;       XB_SPIN(xb_ld(&bar[XB_XGEN(b.x)]) == gen, bar);
;       __builtin_amdgcn_fence(__ATOMIC_ACQUIRE, "agent");
;       asm volatile("s_waitcnt vmcnt(0)" ::: "memory");
;     }
.LBB0_1125:
	s_waitcnt lgkmcnt(0)
	v_readfirstlane_b32 s2, v2
	v_readfirstlane_b32 s3, v0
	v_readlane_b32 s4, v240, 5
	s_lshl_b32 s4, s4, 8
	s_addk_i32 s4, 0x1400
	v_mov_b32_e32 v1, s4
	v_mov_b32_e32 v3, 1
	global_atomic_add v3, v1, v3, s[82:83] sc0
	s_mul_i32 s2, s2, 6
	s_mul_i32 s3, s3, 6
	v_readlane_b32 s4, v240, 42
	s_and_b32 s4, s4, 15
	s_lshl_b32 s4, s4, 8
	s_addk_i32 s4, 0x2400
	s_waitcnt vmcnt(0)
	v_readfirstlane_b32 s5, v3
	s_add_i32 s5, s5, 1
	s_cmp_lg_u32 s5, s2
	s_cbranch_scc1 .Lxb7_nm
	buffer_wbl2 sc1
	buffer_inv sc1
	s_waitcnt vmcnt(0)
	s_mov_b64 exec, 0xffff
	v_mbcnt_lo_u32_b32 v1, -1, 0
	v_lshlrev_b32_e32 v1, 8, v1
	v_add_u32_e32 v1, 0x2400, v1
	v_mov_b32_e32 v3, 1
	global_atomic_add v1, v3, s[82:83]
	s_mov_b64 exec, 1
	s_branch .Lxb7_wait

; __device__ __forceinline__ unsigned xb_ld(unsigned* p)              { return __hip_atomic_load(p, __ATOMIC_RELAXED, __HIP_MEMORY_SCOPE_AGENT); }
; __device__ __forceinline__ unsigned xb_add(unsigned* p, unsigned v) { return __hip_atomic_fetch_add(p, v, __ATOMIC_RELAXED, __HIP_MEMORY_SCOPE_AGENT); }
; #define XB_SPIN(cond, bar) do { unsigned _sp = 0; while (cond) { __builtin_amdgcn_s_sleep(1); \
;     if ((++_sp & 255u) == 0u) { if (xb_ld(&(bar)[XB_TMO])) break; if (_sp > XB_SPIN_CAP) { atomicAdd(&(bar)[XB_TMO], 1u); break; } } } } while (0)
; __device__ void phaseD(const Params& p, char* smem) {
;     ...
;   const int tid = threadIdx.x, lane = tid & 63, w = tid >> 6, l15 = lane & 15, kg = lane >> 4;
;   for (int g = blockIdx.x; g < NTOK / 16; g += gridDim.x) {
;     const int row0 = g * 16;
;     {
;       float4 v[4][4];
; #pragma unroll
;       for (int i = 0; i < 4; i++)
; #pragma unroll
;         for (int j = 0; j < 4; j++) {
;           const int row = row0 + w * 4 + i;
;           const float* zr = ((row & 2047) >= 896) ? (p.Z + (size_t)row * DM) : (p.LF + ((size_t)((row >> 11) * 1024 + (row & 1023))) * DM);
;           v[i][j] = *(const float4*)&zr[lane * 4 + 256 * j];
;         }
; __device__ __forceinline__ void xcd_barrier(const XcdBarrier& b) {
;     ...
;     unsigned nloc = b.st[0], nx = b.st[1];
;     if (nloc == 0u) { xcd_barrier_complete(bar, b.x, nloc, nx); b.st[0] = nloc; b.st[1] = nx; }
;     const unsigned old = xb_add(&bar[XB_XSUB(b.x)], 1u);
;     const unsigned gen = old / nloc;
;     if (old + 1u == (gen + 1u) * nloc) {
;       __builtin_amdgcn_fence(__ATOMIC_RELEASE, "agent");
;       asm volatile("s_waitcnt vmcnt(0)" ::: "memory");
;       const unsigned og = xb_add(&bar[XB_TOP], 1u);
;       const unsigned tg = og / nx;
;       if (og + 1u == (tg + 1u) * nx) xb_add(&bar[XB_TOPGEN], 1u);
;       else XB_SPIN(xb_ld(&bar[XB_TOPGEN]) == tg, bar);
;       __builtin_amdgcn_fence(__ATOMIC_ACQUIRE, "agent");
;       xb_add(&bar[XB_XGEN(b.x)], 1u);
;       asm volatile("s_waitcnt vmcnt(0)" ::: "memory");
;     } else {
;       XB_SPIN(xb_ld(&bar[XB_XGEN(b.x)]) == gen, bar);
;       __builtin_amdgcn_fence(__ATOMIC_ACQUIRE, "agent");
;       asm volatile("s_waitcnt vmcnt(0)" ::: "memory");
;     }
;   }
;   __syncthreads();
; }
.Lxb7_done:
.LBB0_1161:
	s_or_b64 exec, exec, s[0:1]
	v_readlane_b32 s0, v240, 42
	s_movk_i32 s22, 0x3ff
	s_cmpk_gt_i32 s0, 0x3ff
	v_lshlrev_b32_e32 v148, 2, v129
	s_waitcnt lgkmcnt(0)
	s_barrier
	v_readlane_b32 s1, v240, 43
	s_cbranch_scc1 .LBB0_1208
	v_readlane_b32 s36, v240, 26
	v_and_b32_e32 v4, 12, v135
	v_readlane_b32 s37, v240, 27
	v_and_b32_e32 v1, 63, v128
	v_mov_b32_e32 v49, 0
	v_lshl_or_b32 v16, v129, 4, v4
	v_readlane_b32 s38, v240, 28
	v_readlane_b32 s39, v240, 29
	v_readlane_b32 s40, v240, 30
	v_readlane_b32 s41, v240, 31
	v_readlane_b32 s42, v240, 32
	v_readlane_b32 s43, v240, 33
	s_mov_b64 s[12:13], s[36:37]
	v_lshlrev_b32_e32 v2, 8, v129
	v_mul_u32_u24_e32 v21, 0x140, v16
	v_lshlrev_b32_e32 v16, 4, v1
	v_mov_b32_e32 v17, v49
	s_mov_b64 s[14:15], s[38:39]
	v_or_b32_e32 v5, v2, v4
	v_lshl_add_u64 v[52:53], s[12:13], 0, v[16:17]
	v_lshl_add_u64 v[54:55], s[14:15], 0, v[16:17]
	v_lshlrev_b32_e32 v16, 3, v1
	v_or_b32_e32 v6, 1, v5
	v_lshlrev_b32_e32 v50, 2, v136
	s_mov_b64 s[18:19], s[42:43]
	v_lshl_add_u64 v[56:57], s[56:57], 0, v[16:17]
	v_lshlrev_b32_e32 v16, 2, v5
	v_mov_b32_e32 v51, v49
	v_lshlrev_b32_e32 v48, 8, v6
	v_or_b32_e32 v10, 2, v5
	v_lshl_add_u64 v[58:59], s[12:13], 0, v[16:17]
	v_lshl_add_u64 v[60:61], s[14:15], 0, v[16:17]
	v_lshl_add_u64 v[16:17], s[18:19], 0, v[50:51]
	v_lshlrev_b32_e32 v0, 2, v1
	v_cmp_eq_u32_e64 s[6:7], 0, v1
	v_lshlrev_b32_e32 v8, 8, v10
	v_mov_b32_e32 v9, v49
	s_mov_b64 s[16:17], s[40:41]
	v_lshl_add_u64 v[64:65], v[16:17], 0, v[48:49]
	v_lshlrev_b32_e32 v48, 5, v5
	v_or_b32_e32 v1, 32, v5
	v_lshlrev_b32_e32 v6, 5, v6
	v_mov_b32_e32 v7, v49
	v_lshl_add_u64 v[66:67], v[16:17], 0, v[8:9]
	v_lshl_add_u64 v[8:9], s[16:17], 0, v[48:49]
	v_lshlrev_b32_e32 v48, 5, v1
	v_lshlrev_b32_e32 v10, 5, v10
	v_mov_b32_e32 v11, v49
	v_or_b32_e32 v14, 3, v5
	v_lshl_add_u64 v[6:7], s[16:17], 0, v[6:7]
	v_lshl_add_u64 v[78:79], s[16:17], 0, v[48:49]
	v_lshlrev_b32_e32 v48, 8, v1
	v_or_b32_e32 v1, 16, v5
	v_lshl_add_u32 v122, v136, 3, 0
	v_lshlrev_b32_e32 v12, 8, v14
	v_lshlrev_b32_e32 v14, 5, v14
	v_mov_b32_e32 v15, v49
	s_movk_i32 s0, 0x120
	v_lshl_add_u64 v[72:73], v[6:7], 0, v[50:51]
	v_lshl_add_u64 v[6:7], s[16:17], 0, v[10:11]
	v_lshl_add_u64 v[80:81], s[18:19], 0, v[48:49]
	v_lshlrev_b32_e32 v48, 8, v1
	v_lshlrev_b32_e32 v3, 5, v129
	v_mov_b32_e32 v13, v49
	v_sub_u32_e32 v20, v122, v50
	v_mad_u32_u24 v123, v128, s0, 0
	v_lshlrev_b32_e32 v18, 8, v5
	v_mov_b32_e32 v19, v49
	v_lshl_add_u64 v[74:75], v[6:7], 0, v[50:51]
	v_lshl_add_u64 v[6:7], s[16:17], 0, v[14:15]
	s_mov_b64 s[2:3], 0x400
	v_lshl_add_u64 v[86:87], s[18:19], 0, v[48:49]
	v_lshlrev_b32_e32 v48, 5, v1
	v_readlane_b32 s0, v240, 42
	v_cmp_gt_u32_e64 s[8:9], 8, v136
	v_cmp_gt_u32_e64 s[10:11], 16, v128
	v_lshl_add_u64 v[62:63], v[16:17], 0, v[18:19]
	v_lshl_add_u64 v[68:69], v[16:17], 0, v[12:13]
	v_lshl_add_u64 v[70:71], v[8:9], 0, v[50:51]
	v_lshl_add_u64 v[76:77], v[6:7], 0, v[50:51]
	v_lshl_add_u64 v[82:83], v[8:9], 0, s[2:3]
	v_lshl_add_u64 v[84:85], s[18:19], 0, v[18:19]
	v_lshl_add_u64 v[88:89], s[16:17], 0, v[48:49]
	s_movk_i32 s23, 0x37f
	s_movk_i32 s24, 0x3fc
	v_lshlrev_b32_e32 v48, 2, v0
	s_movk_i32 s25, 0x3fd
	s_movk_i32 s26, 0x3fe
	v_mov_b32_e32 v135, 0x3727c5ac
	s_mov_b32 s27, 0x800000
	v_lshlrev_b32_e32 v90, 2, v2
	v_lshlrev_b32_e32 v92, 2, v4
	s_mov_b64 s[4:5], 0x2000
	v_add_u32_e32 v137, v20, v21
	s_mov_b32 s28, 0xe38f
	s_mov_b32 s29, 0xff61b1e6
	s_mov_b32 s30, 0x3fb8aa3b
	s_mov_b32 s31, 0xc2ce8ed0
	s_mov_b32 s36, 0x42b17218
	v_mov_b32_e32 v138, 1
	v_add_u32_e32 v139, 0, v3
	v_mov_b32_e32 v140, 0xff61b1e6
	v_mov_b32_e32 v141, 0x7f800000
	s_mov_b32 s37, s0
	v_readlane_b32 s44, v240, 34
	v_readlane_b32 s45, v240, 35
	v_readlane_b32 s46, v240, 36
	v_readlane_b32 s47, v240, 37
	v_readlane_b32 s48, v240, 38
	v_readlane_b32 s49, v240, 39
	v_readlane_b32 s50, v240, 40
	v_readlane_b32 s51, v240, 41
	v_readlane_b32 s1, v240, 43
	s_branch .LBB0_1166

; __device__ __forceinline__ unsigned xb_ld(unsigned* p)              { return __hip_atomic_load(p, __ATOMIC_RELAXED, __HIP_MEMORY_SCOPE_AGENT); }
; __device__ __forceinline__ unsigned xb_add(unsigned* p, unsigned v) { return __hip_atomic_fetch_add(p, v, __ATOMIC_RELAXED, __HIP_MEMORY_SCOPE_AGENT); }
; #define XB_SPIN(cond, bar) do { unsigned _sp = 0; while (cond) { __builtin_amdgcn_s_sleep(1); \
;     if ((++_sp & 255u) == 0u) { if (xb_ld(&(bar)[XB_TMO])) break; if (_sp > XB_SPIN_CAP) { atomicAdd(&(bar)[XB_TMO], 1u); break; } } } } while (0)
; __device__ __forceinline__ void xcd_barrier(const XcdBarrier& b) {
;     ...
;     unsigned nloc = b.st[0], nx = b.st[1];
;     if (nloc == 0u) { xcd_barrier_complete(bar, b.x, nloc, nx); b.st[0] = nloc; b.st[1] = nx; }
;     const unsigned old = xb_add(&bar[XB_XSUB(b.x)], 1u);
;     const unsigned gen = old / nloc;
;     if (old + 1u == (gen + 1u) * nloc) {
;       __builtin_amdgcn_fence(__ATOMIC_RELEASE, "agent");
;       asm volatile("s_waitcnt vmcnt(0)" ::: "memory");
;       const unsigned og = xb_add(&bar[XB_TOP], 1u);
;       const unsigned tg = og / nx;
;       if (og + 1u == (tg + 1u) * nx) xb_add(&bar[XB_TOPGEN], 1u);
;       else XB_SPIN(xb_ld(&bar[XB_TOPGEN]) == tg, bar);
;       __builtin_amdgcn_fence(__ATOMIC_ACQUIRE, "agent");
;       xb_add(&bar[XB_XGEN(b.x)], 1u);
;       asm volatile("s_waitcnt vmcnt(0)" ::: "memory");
;     } else {
;       XB_SPIN(xb_ld(&bar[XB_XGEN(b.x)]) == gen, bar);
;       __builtin_amdgcn_fence(__ATOMIC_ACQUIRE, "agent");
;       asm volatile("s_waitcnt vmcnt(0)" ::: "memory");
;     }
.LBB0_1224:
	s_waitcnt lgkmcnt(0)
	v_readfirstlane_b32 s2, v2
	v_readfirstlane_b32 s3, v0
	v_readlane_b32 s4, v240, 5
	s_lshl_b32 s4, s4, 8
	s_addk_i32 s4, 0x1400
	v_mov_b32_e32 v1, s4
	v_mov_b32_e32 v3, 1
	global_atomic_add v3, v1, v3, s[82:83] sc0
	s_mul_i32 s2, s2, 7
	s_mul_i32 s3, s3, 7
	v_readlane_b32 s4, v240, 42
	s_and_b32 s4, s4, 15
	s_lshl_b32 s4, s4, 8
	s_addk_i32 s4, 0x2400
	s_waitcnt vmcnt(0)
	v_readfirstlane_b32 s5, v3
	s_add_i32 s5, s5, 1
	s_cmp_lg_u32 s5, s2
	s_cbranch_scc1 .Lxb8_nm
	buffer_wbl2 sc1
	buffer_inv sc1
	s_waitcnt vmcnt(0)
	s_mov_b64 exec, 0xffff
	v_mbcnt_lo_u32_b32 v1, -1, 0
	v_lshlrev_b32_e32 v1, 8, v1
	v_add_u32_e32 v1, 0x2400, v1
	v_mov_b32_e32 v3, 1
	global_atomic_add v1, v3, s[82:83]
	s_mov_b64 exec, 1
	s_branch .Lxb8_wait

; __device__ __forceinline__ unsigned xb_ld(unsigned* p)              { return __hip_atomic_load(p, __ATOMIC_RELAXED, __HIP_MEMORY_SCOPE_AGENT); }
; #define XB_SPIN(cond, bar) do { unsigned _sp = 0; while (cond) { __builtin_amdgcn_s_sleep(1); \
;     if ((++_sp & 255u) == 0u) { if (xb_ld(&(bar)[XB_TMO])) break; if (_sp > XB_SPIN_CAP) { atomicAdd(&(bar)[XB_TMO], 1u); break; } } } } while (0)
; __device__ __forceinline__ void moe_prefix(const Params& p, int* s_off, int* s_rb) {
;   __syncthreads();
;   int* s_cnt = (int*)((char*)s_off - 2 * GEMM_SMEM);
;   if (threadIdx.x < NEXP) s_cnt[threadIdx.x] = p.cnt[threadIdx.x];
;   __syncthreads();
; __device__ __forceinline__ void xcd_barrier(const XcdBarrier& b) {
;     ...
;     } else {
;       XB_SPIN(xb_ld(&bar[XB_XGEN(b.x)]) == gen, bar);
;       __builtin_amdgcn_fence(__ATOMIC_ACQUIRE, "agent");
;       asm volatile("s_waitcnt vmcnt(0)" ::: "memory");
;     }
;   }
;   __syncthreads();
; }
.Lxb8_done:
.LBB0_1260:
	s_or_b64 exec, exec, s[0:1]
	v_lshlrev_b32_e32 v149, 2, v128
	s_waitcnt lgkmcnt(0)
	s_barrier
	s_barrier
	s_and_saveexec_b64 s[0:1], s[52:53]
	s_cbranch_execz .LBB0_1262
	v_lshrrev_b32_e32 v0, 2, v149
	v_mul_u32_u24_e32 v0, 0x20100, v0
	global_load_dword v0, v0, s[62:63]
	s_waitcnt vmcnt(0)
	ds_write_b32 v131, v0

; __device__ __forceinline__ unsigned xb_ld(unsigned* p)              { return __hip_atomic_load(p, __ATOMIC_RELAXED, __HIP_MEMORY_SCOPE_AGENT); }
; __device__ __forceinline__ unsigned xb_add(unsigned* p, unsigned v) { return __hip_atomic_fetch_add(p, v, __ATOMIC_RELAXED, __HIP_MEMORY_SCOPE_AGENT); }
; #define XB_SPIN(cond, bar) do { unsigned _sp = 0; while (cond) { __builtin_amdgcn_s_sleep(1); \
;     if ((++_sp & 255u) == 0u) { if (xb_ld(&(bar)[XB_TMO])) break; if (_sp > XB_SPIN_CAP) { atomicAdd(&(bar)[XB_TMO], 1u); break; } } } } while (0)
; __device__ __forceinline__ void xcd_barrier(const XcdBarrier& b) {
;     ...
;     unsigned nloc = b.st[0], nx = b.st[1];
;     if (nloc == 0u) { xcd_barrier_complete(bar, b.x, nloc, nx); b.st[0] = nloc; b.st[1] = nx; }
;     const unsigned old = xb_add(&bar[XB_XSUB(b.x)], 1u);
;     const unsigned gen = old / nloc;
;     if (old + 1u == (gen + 1u) * nloc) {
;       __builtin_amdgcn_fence(__ATOMIC_RELEASE, "agent");
;       asm volatile("s_waitcnt vmcnt(0)" ::: "memory");
;       const unsigned og = xb_add(&bar[XB_TOP], 1u);
;       const unsigned tg = og / nx;
;       if (og + 1u == (tg + 1u) * nx) xb_add(&bar[XB_TOPGEN], 1u);
;       else XB_SPIN(xb_ld(&bar[XB_TOPGEN]) == tg, bar);
;       __builtin_amdgcn_fence(__ATOMIC_ACQUIRE, "agent");
;       xb_add(&bar[XB_XGEN(b.x)], 1u);
;       asm volatile("s_waitcnt vmcnt(0)" ::: "memory");
;     } else {
;       XB_SPIN(xb_ld(&bar[XB_XGEN(b.x)]) == gen, bar);
;       __builtin_amdgcn_fence(__ATOMIC_ACQUIRE, "agent");
;       asm volatile("s_waitcnt vmcnt(0)" ::: "memory");
;     }
.LBB0_1306:
	s_waitcnt lgkmcnt(0)
	v_readfirstlane_b32 s2, v2
	v_readfirstlane_b32 s3, v0
	v_readlane_b32 s4, v240, 5
	s_lshl_b32 s4, s4, 8
	s_addk_i32 s4, 0x1400
	v_mov_b32_e32 v1, s4
	v_mov_b32_e32 v3, 1
	global_atomic_add v3, v1, v3, s[82:83] sc0
	s_mul_i32 s2, s2, 8
	s_mul_i32 s3, s3, 8
	v_readlane_b32 s4, v240, 42
	s_and_b32 s4, s4, 15
	s_lshl_b32 s4, s4, 8
	s_addk_i32 s4, 0x2400
	s_waitcnt vmcnt(0)
	v_readfirstlane_b32 s5, v3
	s_add_i32 s5, s5, 1
	s_cmp_lg_u32 s5, s2
	s_cbranch_scc1 .Lxb9_nm
	buffer_wbl2 sc1
	buffer_inv sc1
	s_waitcnt vmcnt(0)
	s_mov_b64 exec, 0xffff
	v_mbcnt_lo_u32_b32 v1, -1, 0
	v_lshlrev_b32_e32 v1, 8, v1
	v_add_u32_e32 v1, 0x2400, v1
	v_mov_b32_e32 v3, 1
	global_atomic_add v1, v3, s[82:83]
	s_mov_b64 exec, 1
	s_branch .Lxb9_wait

; __device__ __forceinline__ unsigned xb_ld(unsigned* p)              { return __hip_atomic_load(p, __ATOMIC_RELAXED, __HIP_MEMORY_SCOPE_AGENT); }
; #define XB_SPIN(cond, bar) do { unsigned _sp = 0; while (cond) { __builtin_amdgcn_s_sleep(1); \
;     if ((++_sp & 255u) == 0u) { if (xb_ld(&(bar)[XB_TMO])) break; if (_sp > XB_SPIN_CAP) { atomicAdd(&(bar)[XB_TMO], 1u); break; } } } } while (0)
; __device__ __forceinline__ void moe_prefix(const Params& p, int* s_off, int* s_rb) {
;   __syncthreads();
;   int* s_cnt = (int*)((char*)s_off - 2 * GEMM_SMEM);
;   if (threadIdx.x < NEXP) s_cnt[threadIdx.x] = p.cnt[threadIdx.x];
;   __syncthreads();
; __device__ __forceinline__ void xcd_barrier(const XcdBarrier& b) {
;     ...
;     } else {
;       XB_SPIN(xb_ld(&bar[XB_XGEN(b.x)]) == gen, bar);
;       __builtin_amdgcn_fence(__ATOMIC_ACQUIRE, "agent");
;       asm volatile("s_waitcnt vmcnt(0)" ::: "memory");
;     }
;   }
;   __syncthreads();
; }
.Lxb9_done:
.LBB0_1342:
	s_or_b64 exec, exec, s[0:1]
	s_waitcnt lgkmcnt(0)
	s_barrier
	s_barrier
	s_and_saveexec_b64 s[0:1], s[52:53]
	s_cbranch_execz .LBB0_1344
	v_lshrrev_b32_e32 v0, 2, v149
	v_mul_u32_u24_e32 v0, 0x20100, v0
	global_load_dword v0, v0, s[62:63]
	s_waitcnt vmcnt(0)
	ds_write_b32 v131, v0

; __device__ __forceinline__ unsigned xb_ld(unsigned* p)              { return __hip_atomic_load(p, __ATOMIC_RELAXED, __HIP_MEMORY_SCOPE_AGENT); }
; __device__ __forceinline__ unsigned xb_add(unsigned* p, unsigned v) { return __hip_atomic_fetch_add(p, v, __ATOMIC_RELAXED, __HIP_MEMORY_SCOPE_AGENT); }
; #define XB_SPIN(cond, bar) do { unsigned _sp = 0; while (cond) { __builtin_amdgcn_s_sleep(1); \
;     if ((++_sp & 255u) == 0u) { if (xb_ld(&(bar)[XB_TMO])) break; if (_sp > XB_SPIN_CAP) { atomicAdd(&(bar)[XB_TMO], 1u); break; } } } } while (0)
; __device__ __forceinline__ void xcd_barrier(const XcdBarrier& b) {
;     ...
;     unsigned nloc = b.st[0], nx = b.st[1];
;     if (nloc == 0u) { xcd_barrier_complete(bar, b.x, nloc, nx); b.st[0] = nloc; b.st[1] = nx; }
;     const unsigned old = xb_add(&bar[XB_XSUB(b.x)], 1u);
;     const unsigned gen = old / nloc;
;     if (old + 1u == (gen + 1u) * nloc) {
;       __builtin_amdgcn_fence(__ATOMIC_RELEASE, "agent");
;       asm volatile("s_waitcnt vmcnt(0)" ::: "memory");
;       const unsigned og = xb_add(&bar[XB_TOP], 1u);
;       const unsigned tg = og / nx;
;       if (og + 1u == (tg + 1u) * nx) xb_add(&bar[XB_TOPGEN], 1u);
;       else XB_SPIN(xb_ld(&bar[XB_TOPGEN]) == tg, bar);
;       __builtin_amdgcn_fence(__ATOMIC_ACQUIRE, "agent");
;       xb_add(&bar[XB_XGEN(b.x)], 1u);
;       asm volatile("s_waitcnt vmcnt(0)" ::: "memory");
;     } else {
;       XB_SPIN(xb_ld(&bar[XB_XGEN(b.x)]) == gen, bar);
;       __builtin_amdgcn_fence(__ATOMIC_ACQUIRE, "agent");
;       asm volatile("s_waitcnt vmcnt(0)" ::: "memory");
;     }
.LBB0_1388:
	s_waitcnt lgkmcnt(0)
	v_readfirstlane_b32 s2, v2
	v_readfirstlane_b32 s3, v0
	v_readlane_b32 s4, v240, 5
	s_lshl_b32 s4, s4, 8
	s_addk_i32 s4, 0x1400
	v_mov_b32_e32 v1, s4
	v_mov_b32_e32 v3, 1
	global_atomic_add v3, v1, v3, s[82:83] sc0
	s_mul_i32 s2, s2, 9
	s_mul_i32 s3, s3, 9
	v_readlane_b32 s4, v240, 42
	s_and_b32 s4, s4, 15
	s_lshl_b32 s4, s4, 8
	s_addk_i32 s4, 0x2400
	s_waitcnt vmcnt(0)
	v_readfirstlane_b32 s5, v3
	s_add_i32 s5, s5, 1
	s_cmp_lg_u32 s5, s2
	s_cbranch_scc1 .Lxb10_nm
	buffer_wbl2 sc1
	buffer_inv sc1
	s_waitcnt vmcnt(0)
	s_mov_b64 exec, 0xffff
	v_mbcnt_lo_u32_b32 v1, -1, 0
	v_lshlrev_b32_e32 v1, 8, v1
	v_add_u32_e32 v1, 0x2400, v1
	v_mov_b32_e32 v3, 1
	global_atomic_add v1, v3, s[82:83]
	s_mov_b64 exec, 1
	s_branch .Lxb10_wait
